# grid barrier: waiting workgroups poll the top-level generation word directly; per-XCD generation bump dropped
# baseline (speedup 1.0000x reference)
.LBB0_1138:
	s_or_b64 exec, exec, s[2:3]
	v_cvt_f32_u32_e32 v5, v3
	s_waitcnt vmcnt(0)
	v_readfirstlane_b32 s2, v4
	v_sub_u32_e32 v4, 0, v3
	v_rcp_iflag_f32_e32 v5, v5
	v_add_u32_e32 v6, s2, v1
	v_mul_f32_e32 v5, 0x4f7ffffe, v5
	v_cvt_u32_f32_e32 v5, v5
	v_mul_lo_u32 v1, v4, v5
	v_mul_hi_u32 v1, v5, v1
	v_add_u32_e32 v1, v5, v1
	v_mul_hi_u32 v1, v6, v1
	v_mul_lo_u32 v4, v1, v3
	v_sub_u32_e32 v4, v6, v4
	v_add_u32_e32 v5, 1, v1
	v_cmp_ge_u32_e32 vcc, v4, v3
	s_nop 1
	v_cndmask_b32_e32 v1, v1, v5, vcc
	v_sub_u32_e32 v5, v4, v3
	v_cndmask_b32_e32 v4, v4, v5, vcc
	v_add_u32_e32 v5, 1, v1
	v_cmp_ge_u32_e32 vcc, v4, v3
	v_add_u32_e32 v4, 1, v6
	s_nop 0
	v_cndmask_b32_e32 v1, v1, v5, vcc
	v_mul_lo_u32 v5, v3, v1
	v_add_u32_e32 v3, v5, v3
	v_cmp_ne_u32_e32 vcc, v4, v3
	s_and_saveexec_b64 s[2:3], vcc
	s_xor_b64 s[2:3], exec, s[2:3]
	s_cbranch_execz .LBB0_1152
	v_readlane_b32 s4, v252, 10
	v_readlane_b32 s5, v252, 11
	s_waitcnt lgkmcnt(0)
	s_nop 3
	global_load_dword v2, v0, s[4:5] sc1
	s_waitcnt vmcnt(0)
	v_cmp_eq_u32_e32 vcc, v2, v1
	s_and_saveexec_b64 s[4:5], vcc
	s_cbranch_execz .LBB0_1151
	s_mov_b32 s20, 1
	s_mov_b64 s[6:7], 0
	s_branch .LBB0_1142

.LBB0_1169:
	s_or_b64 exec, exec, s[2:3]
	s_mov_b64 s[2:3], exec
	v_mbcnt_lo_u32_b32 v1, s2, 0
	v_mbcnt_hi_u32_b32 v1, s3, v1
	v_cmp_eq_u32_e32 vcc, 0, v1
	s_waitcnt vmcnt(0)
	buffer_inv sc1
	s_and_saveexec_b64 s[4:5], vcc
	s_cbranch_execz .LBB0_1171
	s_bcnt1_i32_b64 s2, s[2:3]
	v_mov_b32_e32 v1, s2
	v_readlane_b32 s2, v252, 6
	v_readlane_b32 s3, v252, 7
	s_nop 4
.LBB0_1171:
	s_or_b64 exec, exec, s[4:5]
	s_waitcnt vmcnt(0)
